# scan producer applies the block-cumulative decay scaling in registers before its LDS writes (no LDS post-pass in the chunk loop)
# speedup vs baseline: 1.0153x; 1.0153x over previous
; DI void scan_item(PP p, int l, int item, LAS unsigned char* lds) {
;     ...
;         for (int i = 0; i < 8; ++i) { kk[i] = pk_[i] * kkw; n2[i] = kk[i] * kk[i]; }
; #pragma unroll
;         for (int i = 0; i < 8; ++i) n2[i] += dpp_f(n2[i], 0);
; #pragma unroll
;         for (int i = 0; i < 8; ++i) n2[i] += dpp_f(n2[i], 1);
; #pragma unroll
;         for (int i = 0; i < 8; ++i) n2[i] += dpp_f(n2[i], 2);
; #pragma unroll
;         for (int i = 0; i < 8; ++i) n2[i] += dpp_f(n2[i], 3);
; #pragma unroll
;         for (int i = 0; i < 8; ++i) n2[i] += __shfl_xor(n2[i], 16);
; #pragma unroll
;         for (int i = 0; i < 8; ++i) n2[i] += __shfl_xor(n2[i], 32);
; #pragma unroll
;         for (int i = 0; i < 8; ++i) {
;             const float kn = kk[i] * __builtin_amdgcn_rsqf(fmaxf(n2[i], 1e-24f));
.LBB0_265:
	s_and_b64 vcc, exec, s[6:7]
	s_cbranch_vccz .LBB0_251
	s_cmpk_eq_i32 s30, 0x47
	s_cbranch_scc1 .LBB0_252
	s_waitcnt vmcnt(1)
	v_mul_f32_e32 v0, v117, v82
	v_mul_f32_e32 v1, v0, v0
	v_and_b32_e32 v17, 64, v185
	v_xor_b32_e32 v16, 16, v185
	v_mov_b32_dpp v1, v1 quad_perm:[1,0,3,2] row_mask:0xf bank_mask:0xf bound_ctrl:1
	v_fmac_f32_e32 v1, v0, v0
	v_add_u32_e32 v17, 64, v17
	v_cmp_lt_i32_e32 vcc, v16, v17
	v_add_f32_dpp v1, v1, v1 quad_perm:[2,3,0,1] row_mask:0xf bank_mask:0xf bound_ctrl:1
	v_mul_f32_e32 v2, v117, v83
	v_cndmask_b32_e32 v16, v185, v16, vcc
	v_add_f32_dpp v1, v1, v1 row_half_mirror row_mask:0xf bank_mask:0xf bound_ctrl:1
	v_mul_f32_e32 v3, v2, v2
	v_lshlrev_b32_e32 v16, 2, v16
	v_add_f32_dpp v1, v1, v1 row_mirror row_mask:0xf bank_mask:0xf bound_ctrl:1
	v_mov_b32_dpp v3, v3 quad_perm:[1,0,3,2] row_mask:0xf bank_mask:0xf bound_ctrl:1
	ds_bpermute_b32 v18, v16, v1
	v_fmac_f32_e32 v3, v2, v2
	v_mul_f32_e32 v4, v117, v90
	v_mul_f32_e32 v5, v4, v4
	v_add_f32_dpp v3, v3, v3 quad_perm:[2,3,0,1] row_mask:0xf bank_mask:0xf bound_ctrl:1
	s_waitcnt lgkmcnt(0)
	v_add_f32_e32 v1, v1, v18
	v_mov_b32_dpp v5, v5 quad_perm:[1,0,3,2] row_mask:0xf bank_mask:0xf bound_ctrl:1
	v_add_f32_dpp v3, v3, v3 row_half_mirror row_mask:0xf bank_mask:0xf bound_ctrl:1
	v_fmac_f32_e32 v5, v4, v4
	v_mul_f32_e32 v6, v117, v91
	v_add_f32_dpp v3, v3, v3 row_mirror row_mask:0xf bank_mask:0xf bound_ctrl:1
	ds_bpermute_b32 v18, v16, v3
	v_add_f32_dpp v5, v5, v5 quad_perm:[2,3,0,1] row_mask:0xf bank_mask:0xf bound_ctrl:1
	v_mul_f32_e32 v7, v6, v6
	v_mul_f32_e32 v8, v117, v98
	v_add_f32_dpp v5, v5, v5 row_half_mirror row_mask:0xf bank_mask:0xf bound_ctrl:1
	v_mov_b32_dpp v7, v7 quad_perm:[1,0,3,2] row_mask:0xf bank_mask:0xf bound_ctrl:1
	s_waitcnt lgkmcnt(0)
	v_add_f32_e32 v3, v3, v18
	v_add_f32_dpp v5, v5, v5 row_mirror row_mask:0xf bank_mask:0xf bound_ctrl:1
	ds_bpermute_b32 v18, v16, v5
	v_fmac_f32_e32 v7, v6, v6
	v_mul_f32_e32 v9, v8, v8
	v_mul_f32_e32 v10, v117, v99
	v_add_f32_dpp v7, v7, v7 quad_perm:[2,3,0,1] row_mask:0xf bank_mask:0xf bound_ctrl:1
	v_mov_b32_dpp v9, v9 quad_perm:[1,0,3,2] row_mask:0xf bank_mask:0xf bound_ctrl:1
	s_waitcnt lgkmcnt(0)
	v_add_f32_e32 v5, v5, v18
	v_add_f32_dpp v7, v7, v7 row_half_mirror row_mask:0xf bank_mask:0xf bound_ctrl:1
	v_fmac_f32_e32 v9, v8, v8
	v_mul_f32_e32 v11, v10, v10
	v_add_f32_dpp v7, v7, v7 row_mirror row_mask:0xf bank_mask:0xf bound_ctrl:1
	ds_bpermute_b32 v18, v16, v7
	v_add_f32_dpp v9, v9, v9 quad_perm:[2,3,0,1] row_mask:0xf bank_mask:0xf bound_ctrl:1
	v_mov_b32_dpp v11, v11 quad_perm:[1,0,3,2] row_mask:0xf bank_mask:0xf bound_ctrl:1
	v_fmac_f32_e32 v11, v10, v10
	v_add_f32_dpp v9, v9, v9 row_half_mirror row_mask:0xf bank_mask:0xf bound_ctrl:1
	s_waitcnt lgkmcnt(0)
	v_add_f32_e32 v7, v7, v18
	v_add_f32_dpp v11, v11, v11 quad_perm:[2,3,0,1] row_mask:0xf bank_mask:0xf bound_ctrl:1
	v_add_f32_dpp v9, v9, v9 row_mirror row_mask:0xf bank_mask:0xf bound_ctrl:1
	ds_bpermute_b32 v18, v16, v9
	v_mul_f32_e32 v12, v117, v106
	v_mul_f32_e32 v14, v117, v107
	v_add_f32_dpp v11, v11, v11 row_half_mirror row_mask:0xf bank_mask:0xf bound_ctrl:1
	v_mul_f32_e32 v13, v12, v12
	v_mul_f32_e32 v15, v14, v14
	v_add_f32_dpp v11, v11, v11 row_mirror row_mask:0xf bank_mask:0xf bound_ctrl:1
	v_mov_b32_dpp v13, v13 quad_perm:[1,0,3,2] row_mask:0xf bank_mask:0xf bound_ctrl:1
	v_mov_b32_dpp v15, v15 quad_perm:[1,0,3,2] row_mask:0xf bank_mask:0xf bound_ctrl:1
	s_waitcnt lgkmcnt(0)
	v_add_f32_e32 v9, v9, v18
	ds_bpermute_b32 v18, v16, v11
	v_fmac_f32_e32 v13, v12, v12
	v_fmac_f32_e32 v15, v14, v14
	s_lshl_b32 s6, s30, 31
	v_add_f32_dpp v13, v13, v13 quad_perm:[2,3,0,1] row_mask:0xf bank_mask:0xf bound_ctrl:1
	v_add_f32_dpp v15, v15, v15 quad_perm:[2,3,0,1] row_mask:0xf bank_mask:0xf bound_ctrl:1
	s_waitcnt lgkmcnt(0)
	v_add_f32_e32 v11, v11, v18
	v_add_f32_dpp v13, v13, v13 row_half_mirror row_mask:0xf bank_mask:0xf bound_ctrl:1
	v_add_f32_dpp v15, v15, v15 row_half_mirror row_mask:0xf bank_mask:0xf bound_ctrl:1
	s_ashr_i32 s6, s6, 26
	v_add_f32_dpp v13, v13, v13 row_mirror row_mask:0xf bank_mask:0xf bound_ctrl:1
	v_add_f32_dpp v15, v15, v15 row_mirror row_mask:0xf bank_mask:0xf bound_ctrl:1
	ds_bpermute_b32 v18, v16, v13
	ds_bpermute_b32 v16, v16, v15
	s_add_i32 s6, s6, s52
	s_mulk_i32 s6, 0x600
	s_cmpk_gt_u32 s30, 0x45
	s_waitcnt lgkmcnt(1)
	v_add_f32_e32 v13, v13, v18
	s_waitcnt lgkmcnt(0)
	v_add_f32_e32 v15, v15, v16
	v_xor_b32_e32 v16, 32, v185
	v_cmp_lt_i32_e32 vcc, v16, v17
	s_nop 1
	v_cndmask_b32_e32 v16, v185, v16, vcc
	v_lshlrev_b32_e32 v16, 2, v16
	ds_bpermute_b32 v17, v16, v1
	s_waitcnt lgkmcnt(0)
	v_add_f32_e32 v1, v1, v17
	ds_bpermute_b32 v17, v16, v3
	v_max_f32_e32 v1, 0x179abe15, v1
	v_rsq_f32_e32 v1, v1
	s_waitcnt lgkmcnt(0)
	v_add_f32_e32 v3, v3, v17
	ds_bpermute_b32 v17, v16, v5
	v_mul_f32_e64 v0, v0, -v1
	v_add_f32_e32 v1, -1.0, v88
	s_waitcnt vmcnt(0)
	v_fma_f32 v1, v129, v1, 1.0
	v_mul_f32_e32 v1, v83, v1
	s_waitcnt lgkmcnt(0)
	v_add_f32_e32 v5, v5, v17
	ds_bpermute_b32 v17, v16, v7
	s_waitcnt lgkmcnt(0)
	v_add_f32_e32 v7, v7, v17
	ds_bpermute_b32 v17, v16, v9
	s_waitcnt lgkmcnt(0)
	v_add_f32_e32 v9, v9, v17
	ds_bpermute_b32 v17, v16, v11
	s_waitcnt lgkmcnt(0)
	v_add_f32_e32 v11, v11, v17
	ds_bpermute_b32 v17, v16, v13
	ds_bpermute_b32 v16, v16, v15
	s_waitcnt lgkmcnt(1)
	v_add_f32_e32 v13, v13, v17
	v_add_f32_e32 v17, -1.0, v89
	v_fma_f32 v17, v129, v17, 1.0
	s_waitcnt lgkmcnt(0)
; #define LAS __attribute__((address_space(3)))
; DI float bf2f(u16 b) { return __uint_as_float(((unsigned)b) << 16); }
; DI void scan_item(PP p, int l, int item, LAS unsigned char* lds) {
;     ...
;     auto gl = [&](int c) {
;         const int pw = wid - 4;
;         const int row0 = steprow(b, dir, c * T + pw * 8); const int rs = dir ? -1 : 1;
; #pragma unroll
;         for (int i = 0; i < 8; ++i) { const size_t o = (size_t)(row0 + rs * i) * 512 + ch;
;             pr_[i] = bf2f(RKV[o]); pk_[i] = bf2f(RKV[(size_t)NTOK * 512 + o]); pv_[i] = bf2f(RKV[(size_t)2 * NTOK * 512 + o]); pd_[i] = DEC[o]; pa_[i] = bf2f(AA[o]); }
;     };
;     ...
;         for (int i = 0; i < 8; ++i) {
;             const float kn = kk[i] * __builtin_amdgcn_rsqf(fmaxf(n2[i], 1e-24f));
;             LAS float* d = buf + ((c & 1) * T + pw * 8 + i) * 384 + lane;
;             d[0] = pr_[i]; d[64] = pd_[i]; d[128] = pk_[i] * (1.0f + (pa_[i] - 1.0f) * kaw); d[192] = -kn; d[256] = kn * pa_[i]; d[320] = pv_[i];
;         }
	v_add_f32_e32 v15, v15, v16
	v_add_u32_e32 v16, s6, v140
	v_mul_f32_e32 v17, v82, v17
	v_mul_f32_e32 v131, v131, v130
	v_mul_f32_e32 v132, v132, v131
	v_mul_f32_e32 v133, v133, v132
	v_mul_f32_e32 v134, v134, v133
	v_mul_f32_e32 v135, v135, v134
	v_mul_f32_e32 v141, v141, v135
	v_mul_f32_e32 v152, v152, v141
	v_rcp_f32_e32 v118, v130
	v_rcp_f32_e32 v119, v131
	v_rcp_f32_e32 v120, v132
	v_rcp_f32_e32 v121, v133
	v_rcp_f32_e32 v122, v134
	v_rcp_f32_e32 v123, v135
	v_rcp_f32_e32 v124, v141
	v_rcp_f32_e32 v125, v152
	v_mul_f32_e32 v85, v85, v130
	v_mul_f32_e32 v84, v84, v131
	v_mul_f32_e32 v93, v93, v132
	v_mul_f32_e32 v92, v92, v133
	v_mul_f32_e32 v103, v103, v134
	v_mul_f32_e32 v102, v102, v135
	v_mul_f32_e32 v111, v111, v141
	v_mul_f32_e32 v110, v110, v152
	v_mul_f32_e32 v17, v17, v118
	ds_write2st64_b32 v16, v17, v0 offset0:2 offset1:3
	v_mul_f32_e64 v0, v89, -v0
	v_mul_f32_e32 v127, v0, v118
	ds_write2st64_b32 v16, v127, v87 offset0:4 offset1:5
	v_max_f32_e32 v0, 0x179abe15, v3
	v_rsq_f32_e32 v0, v0
	ds_write2st64_b32 v16, v85, v130 offset1:1
	ds_write2st64_b32 v16, v84, v131 offset0:6 offset1:7
	ds_write2st64_b32 v16, v93, v132 offset0:12 offset1:13
	v_mul_f32_e64 v0, v2, -v0
	v_mul_f32_e32 v1, v1, v119
	v_mul_f32_e32 v126, v0, v130
	ds_write2st64_b32 v16, v1, v126 offset0:8 offset1:9
	v_mul_f32_e64 v0, v88, -v0
	v_mul_f32_e32 v127, v0, v119
	ds_write2st64_b32 v16, v127, v86 offset0:10 offset1:11
	v_max_f32_e32 v0, 0x179abe15, v5
	v_rsq_f32_e32 v0, v0
	v_add_f32_e32 v1, -1.0, v101
	v_fma_f32 v1, v129, v1, 1.0
	v_mul_f32_e32 v1, v90, v1
	v_mul_f32_e64 v0, v4, -v0
	v_mul_f32_e32 v1, v1, v120
	v_mul_f32_e32 v126, v0, v131
	ds_write2st64_b32 v16, v1, v126 offset0:14 offset1:15
	v_mul_f32_e64 v0, v101, -v0
	v_mul_f32_e32 v127, v0, v120
	ds_write2st64_b32 v16, v127, v95 offset0:16 offset1:17
	v_max_f32_e32 v0, 0x179abe15, v7
	v_rsq_f32_e32 v0, v0
	v_add_f32_e32 v1, -1.0, v100
	v_fma_f32 v1, v129, v1, 1.0
	v_mul_f32_e32 v1, v91, v1
	v_mul_f32_e64 v0, v6, -v0
	v_mul_f32_e32 v1, v1, v121
	v_mul_f32_e32 v126, v0, v132
	ds_write2st64_b32 v16, v1, v126 offset0:20 offset1:21
	v_mul_f32_e64 v0, v100, -v0
	v_mul_f32_e32 v127, v0, v121
	ds_write2st64_b32 v16, v127, v94 offset0:22 offset1:23
	v_max_f32_e32 v0, 0x179abe15, v9
	v_rsq_f32_e32 v0, v0
	v_add_f32_e32 v1, -1.0, v109
	v_fma_f32 v1, v129, v1, 1.0
	v_mul_f32_e32 v1, v98, v1
	v_mul_f32_e64 v0, v8, -v0
	v_mul_f32_e32 v1, v1, v122
	v_mul_f32_e32 v126, v0, v133
	ds_write2st64_b32 v16, v1, v126 offset0:26 offset1:27
	v_mul_f32_e64 v0, v109, -v0
	v_mul_f32_e32 v127, v0, v122
	ds_write2st64_b32 v16, v127, v105 offset0:28 offset1:29
	v_max_f32_e32 v0, 0x179abe15, v11
	v_rsq_f32_e32 v0, v0
	v_add_f32_e32 v1, -1.0, v108
	v_fma_f32 v1, v129, v1, 1.0
	v_mul_f32_e32 v1, v99, v1
	v_mul_f32_e64 v0, v10, -v0
	v_mul_f32_e32 v1, v1, v123
	v_mul_f32_e32 v126, v0, v134
	ds_write2st64_b32 v16, v1, v126 offset0:32 offset1:33
	v_mul_f32_e64 v0, v108, -v0
	v_mul_f32_e32 v127, v0, v123
	ds_write2st64_b32 v16, v127, v104 offset0:34 offset1:35
	v_max_f32_e32 v0, 0x179abe15, v13
	v_rsq_f32_e32 v0, v0
	v_add_f32_e32 v1, -1.0, v115
	v_fma_f32 v1, v129, v1, 1.0
	v_mul_f32_e32 v1, v106, v1
	v_mul_f32_e64 v0, v12, -v0
	v_mul_f32_e32 v1, v1, v124
	v_mul_f32_e32 v126, v0, v135
	ds_write2st64_b32 v16, v1, v126 offset0:38 offset1:39
	v_mul_f32_e64 v0, v115, -v0
	v_mul_f32_e32 v127, v0, v124
	ds_write2st64_b32 v16, v127, v113 offset0:40 offset1:41
	v_max_f32_e32 v0, 0x179abe15, v15
	v_rsq_f32_e32 v0, v0
	v_add_f32_e32 v1, -1.0, v114
	v_fma_f32 v1, v129, v1, 1.0
	v_mul_f32_e32 v1, v107, v1
	v_mul_f32_e64 v0, v14, -v0
	v_mul_f32_e32 v1, v1, v125
	v_mul_f32_e32 v126, v0, v141
	ds_write2st64_b32 v16, v1, v126 offset0:44 offset1:45
	v_mul_f32_e64 v0, v114, -v0
	ds_write2st64_b32 v16, v92, v133 offset0:18 offset1:19
	ds_write2st64_b32 v16, v103, v134 offset0:24 offset1:25
	ds_write2st64_b32 v16, v102, v135 offset0:30 offset1:31
	ds_write2st64_b32 v16, v111, v141 offset0:36 offset1:37
	ds_write2st64_b32 v16, v110, v152 offset0:42 offset1:43
	v_mul_f32_e32 v127, v0, v125
	ds_write2st64_b32 v16, v127, v112 offset0:46 offset1:47
	s_cbranch_scc1 .LBB0_252
	s_lshl_b32 s6, s30, 5
	s_add_i32 s6, s54, s6
	s_add_i32 s7, s6, 0xffffff00
	s_cmpk_lt_i32 s6, 0x100
	s_movk_i32 s3, 0x8ff
	s_cselect_b32 s8, 0xff, s3
	s_cselect_b32 s9, s6, s7
	s_cselect_b32 s68, s24, s53
	s_sub_i32 s8, s8, s6
	s_and_b64 s[6:7], s[46:47], exec
	s_cselect_b32 s6, s9, s8
	s_add_i32 s6, s6, s68
	s_ashr_i32 s7, s6, 31
	s_lshl_b64 s[8:9], s[6:7], 9
	v_lshl_add_u64 v[0:1], s[8:9], 0, v[96:97]
	s_add_i32 s8, s6, s55
	s_ashr_i32 s9, s8, 31
	v_lshlrev_b64 v[2:3], 1, v[0:1]
	s_lshl_b64 s[8:9], s[8:9], 9
	v_lshl_add_u64 v[4:5], s[4:5], 0, v[2:3]
	s_mov_b32 s68, 0x1200000
	v_lshl_add_u64 v[8:9], s[8:9], 0, v[96:97]
	v_add_co_u32_e32 v6, vcc, s68, v4
	v_lshlrev_b64 v[10:11], 1, v[8:9]
	s_nop 0
	v_addc_co_u32_e32 v7, vcc, 0, v5, vcc
	v_lshl_add_u64 v[12:13], s[4:5], 0, v[10:11]
	v_add_co_u32_e32 v14, vcc, s68, v12
	s_mov_b32 s3, 0x2400000
	s_nop 0
	v_addc_co_u32_e32 v15, vcc, 0, v13, vcc
	v_add_co_u32_e32 v16, vcc, s3, v12
	s_add_i32 s8, s6, s56
	s_nop 0
	v_addc_co_u32_e32 v17, vcc, 0, v13, vcc
	s_ashr_i32 s9, s8, 31
	v_add_co_u32_e32 v18, vcc, s3, v4
	s_lshl_b64 s[8:9], s[8:9], 9
	v_lshl_add_u64 v[0:1], v[0:1], 2, s[36:37]
	v_lshl_add_u64 v[2:3], s[42:43], 0, v[2:3]
	v_addc_co_u32_e32 v19, vcc, 0, v5, vcc
	global_load_ushort v26, v[6:7], off
	global_load_dword v130, v[0:1], off
	global_load_ushort v27, v[12:13], off
	global_load_ushort v28, v[14:15], off
	global_load_ushort v29, v[16:17], off
	global_load_ushort v30, v[18:19], off
	global_load_ushort v31, v[2:3], off
; DI float bf2f(u16 b) { return __uint_as_float(((unsigned)b) << 16); }
; DI void scan_item(PP p, int l, int item, LAS unsigned char* lds) {
;     ...
;     auto gl = [&](int c) {
;         const int pw = wid - 4;
;         const int row0 = steprow(b, dir, c * T + pw * 8); const int rs = dir ? -1 : 1;
; #pragma unroll
;         for (int i = 0; i < 8; ++i) { const size_t o = (size_t)(row0 + rs * i) * 512 + ch;
;             pr_[i] = bf2f(RKV[o]); pk_[i] = bf2f(RKV[(size_t)NTOK * 512 + o]); pv_[i] = bf2f(RKV[(size_t)2 * NTOK * 512 + o]); pd_[i] = DEC[o]; pa_[i] = bf2f(AA[o]); }
;     };
	global_load_ushort v32, v[4:5], off
	v_lshl_add_u64 v[4:5], s[8:9], 0, v[96:97]
	s_add_i32 s8, s6, s57
	s_ashr_i32 s9, s8, 31
	v_lshlrev_b64 v[6:7], 1, v[4:5]
	s_lshl_b64 s[8:9], s[8:9], 9
	v_lshl_add_u64 v[0:1], v[8:9], 2, s[36:37]
	v_lshl_add_u64 v[8:9], s[4:5], 0, v[6:7]
	v_lshl_add_u64 v[12:13], s[8:9], 0, v[96:97]
	v_lshl_add_u64 v[2:3], s[42:43], 0, v[10:11]
	v_add_co_u32_e32 v10, vcc, s68, v8
	v_lshlrev_b64 v[14:15], 1, v[12:13]
	s_nop 0
	v_addc_co_u32_e32 v11, vcc, 0, v9, vcc
	v_lshl_add_u64 v[16:17], s[4:5], 0, v[14:15]
	v_add_co_u32_e32 v18, vcc, s68, v16
	v_lshl_add_u64 v[4:5], v[4:5], 2, s[36:37]
	s_nop 0
	v_addc_co_u32_e32 v19, vcc, 0, v17, vcc
	v_lshl_add_u64 v[6:7], s[42:43], 0, v[6:7]
	global_load_dword v131, v[0:1], off
	global_load_ushort v33, v[2:3], off
	global_load_ushort v34, v[10:11], off
	global_load_dword v132, v[4:5], off
	global_load_ushort v35, v[16:17], off
	global_load_ushort v36, v[18:19], off
	global_load_ushort v37, v[6:7], off
	global_load_ushort v38, v[8:9], off
	v_add_co_u32_e32 v0, vcc, s3, v16
	s_add_i32 s8, s6, s58
	s_nop 0
	v_addc_co_u32_e32 v1, vcc, 0, v17, vcc
	s_ashr_i32 s9, s8, 31
	v_add_co_u32_e32 v2, vcc, s3, v8
	s_lshl_b64 s[8:9], s[8:9], 9
	s_nop 0
	v_addc_co_u32_e32 v3, vcc, 0, v9, vcc
	v_lshl_add_u64 v[8:9], s[8:9], 0, v[96:97]
	s_add_i32 s8, s6, s59
	s_ashr_i32 s9, s8, 31
	v_lshlrev_b64 v[10:11], 1, v[8:9]
	s_lshl_b64 s[8:9], s[8:9], 9
	v_lshl_add_u64 v[4:5], v[12:13], 2, s[36:37]
	v_lshl_add_u64 v[12:13], s[4:5], 0, v[10:11]
	v_lshl_add_u64 v[16:17], s[8:9], 0, v[96:97]
	v_lshl_add_u64 v[6:7], s[42:43], 0, v[14:15]
	v_add_co_u32_e32 v14, vcc, s68, v12
	v_lshlrev_b64 v[18:19], 1, v[16:17]
	s_nop 0
	v_addc_co_u32_e32 v15, vcc, 0, v13, vcc
	v_lshl_add_u64 v[20:21], s[4:5], 0, v[18:19]
	v_lshl_add_u64 v[8:9], v[8:9], 2, s[36:37]
	v_lshl_add_u64 v[10:11], s[42:43], 0, v[10:11]
	global_load_ushort v39, v[0:1], off
	global_load_ushort v40, v[2:3], off
	global_load_dword v133, v[4:5], off
	global_load_ushort v41, v[6:7], off
	global_load_ushort v42, v[14:15], off
	global_load_dword v134, v[8:9], off
	global_load_ushort v43, v[10:11], off
	global_load_ushort v44, v[12:13], off
	v_add_co_u32_e32 v0, vcc, s68, v20
	s_add_i32 s8, s6, s60
	s_nop 0
	v_addc_co_u32_e32 v1, vcc, 0, v21, vcc
	v_add_co_u32_e32 v2, vcc, s3, v20
	s_ashr_i32 s9, s8, 31
	s_nop 0
	v_addc_co_u32_e32 v3, vcc, 0, v21, vcc
	s_lshl_b64 s[8:9], s[8:9], 9
	s_add_i32 s6, s6, s61
	v_add_co_u32_e32 v4, vcc, s3, v12
	v_lshl_add_u64 v[10:11], s[8:9], 0, v[96:97]
	s_ashr_i32 s7, s6, 31
	v_addc_co_u32_e32 v5, vcc, 0, v13, vcc
	v_lshlrev_b64 v[12:13], 1, v[10:11]
	s_lshl_b64 s[6:7], s[6:7], 9
	v_lshl_add_u64 v[8:9], s[42:43], 0, v[18:19]
	v_lshl_add_u64 v[14:15], s[4:5], 0, v[12:13]
	v_lshl_add_u64 v[18:19], s[6:7], 0, v[96:97]
	v_lshl_add_u64 v[6:7], v[16:17], 2, s[36:37]
	v_add_co_u32_e32 v16, vcc, s68, v14
	v_lshlrev_b64 v[22:23], 1, v[18:19]
	s_nop 0
	v_addc_co_u32_e32 v17, vcc, 0, v15, vcc
	v_lshl_add_u64 v[24:25], s[4:5], 0, v[22:23]
	global_load_ushort v20, v[20:21], off
	s_nop 0
	global_load_ushort v21, v[0:1], off
	global_load_ushort v45, v[2:3], off
	global_load_ushort v46, v[4:5], off
	global_load_dword v135, v[6:7], off
	global_load_ushort v47, v[8:9], off
	s_nop 0
	global_load_ushort v16, v[16:17], off
	s_nop 0
	global_load_ushort v17, v[14:15], off
	v_add_co_u32_e32 v0, vcc, s68, v24
	v_lshl_add_u64 v[12:13], s[42:43], 0, v[12:13]
	s_nop 0
	v_addc_co_u32_e32 v1, vcc, 0, v25, vcc
	v_add_co_u32_e32 v2, vcc, s3, v24
	v_lshl_add_u64 v[6:7], v[18:19], 2, s[36:37]
	s_nop 0
	v_addc_co_u32_e32 v3, vcc, 0, v25, vcc
	v_add_co_u32_e32 v4, vcc, s3, v14
	v_lshl_add_u64 v[8:9], s[42:43], 0, v[22:23]
	s_nop 0
	v_addc_co_u32_e32 v5, vcc, 0, v15, vcc
	global_load_ushort v14, v[24:25], off
	global_load_ushort v15, v[0:1], off
	s_nop 0
	global_load_ushort v2, v[2:3], off
	s_nop 0
	global_load_ushort v3, v[4:5], off
	global_load_dword v152, v[6:7], off
	s_nop 0
	global_load_ushort v4, v[8:9], off
	global_load_ushort v5, v[12:13], off
	v_lshl_add_u64 v[0:1], v[10:11], 2, s[36:37]
	global_load_dword v141, v[0:1], off
	s_waitcnt vmcnt(32)
	v_lshlrev_b32_e32 v85, 16, v32
	v_lshlrev_b32_e32 v84, 16, v27
	v_lshlrev_b32_e32 v82, 16, v26
	v_lshlrev_b32_e32 v83, 16, v28
	v_lshlrev_b32_e32 v87, 16, v30
	v_lshlrev_b32_e32 v86, 16, v29
	v_lshlrev_b32_e32 v89, 16, v31
	s_waitcnt vmcnt(30)
	v_lshlrev_b32_e32 v88, 16, v33
	s_waitcnt vmcnt(24)
	v_lshlrev_b32_e32 v93, 16, v38
	v_lshlrev_b32_e32 v92, 16, v35
	v_lshlrev_b32_e32 v91, 16, v36
	v_lshlrev_b32_e32 v90, 16, v34
	v_lshlrev_b32_e32 v101, 16, v37
	s_waitcnt vmcnt(23)
	v_lshlrev_b32_e32 v94, 16, v39
	s_waitcnt vmcnt(22)
	v_lshlrev_b32_e32 v95, 16, v40
	s_waitcnt vmcnt(20)
	v_lshlrev_b32_e32 v100, 16, v41
	s_waitcnt vmcnt(19)
	v_lshlrev_b32_e32 v98, 16, v42
	s_waitcnt vmcnt(17)
	v_lshlrev_b32_e32 v109, 16, v43
	s_waitcnt vmcnt(16)
	v_lshlrev_b32_e32 v103, 16, v44
	s_waitcnt vmcnt(15)
	v_lshlrev_b32_e32 v102, 16, v20
	s_waitcnt vmcnt(14)
	v_lshlrev_b32_e32 v99, 16, v21
	s_waitcnt vmcnt(13)
	v_lshlrev_b32_e32 v104, 16, v45
	s_waitcnt vmcnt(12)
	v_lshlrev_b32_e32 v105, 16, v46
	s_waitcnt vmcnt(10)
	v_lshlrev_b32_e32 v108, 16, v47
	s_waitcnt vmcnt(9)
	v_lshlrev_b32_e32 v106, 16, v16
	s_waitcnt vmcnt(8)
	v_lshlrev_b32_e32 v111, 16, v17
	s_waitcnt vmcnt(7)
	v_lshlrev_b32_e32 v110, 16, v14
	s_waitcnt vmcnt(6)
	v_lshlrev_b32_e32 v107, 16, v15
	s_waitcnt vmcnt(5)
	v_lshlrev_b32_e32 v112, 16, v2
	s_waitcnt vmcnt(4)
	v_lshlrev_b32_e32 v113, 16, v3
	s_waitcnt vmcnt(2)
	v_lshlrev_b32_e32 v114, 16, v4
	s_waitcnt vmcnt(1)
	v_lshlrev_b32_e32 v115, 16, v5
	s_branch .LBB0_252
